# grid barrier: the XCD leader bumps its XCD's generation word (releasing the followers) before its own L1 invalidate instead of after; ordering of write-backs vs release unchanged
# baseline (speedup 1.0000x reference)
; __device__ __forceinline__ unsigned xb_ld(unsigned* p)              { return __hip_atomic_load(p, __ATOMIC_RELAXED, __HIP_MEMORY_SCOPE_AGENT); }
; __device__ __forceinline__ unsigned xb_add(unsigned* p, unsigned v) { return __hip_atomic_fetch_add(p, v, __ATOMIC_RELAXED, __HIP_MEMORY_SCOPE_AGENT); }
; #define XB_SPIN(cond, bar) do { unsigned _sp = 0; while (cond) { __builtin_amdgcn_s_sleep(1); \
;     if ((++_sp & 255u) == 0u) { if (xb_ld(&(bar)[XB_TMO])) break; if (_sp > XB_SPIN_CAP) { atomicAdd(&(bar)[XB_TMO], 1u); break; } } } } while (0)
; __device__ __forceinline__ void xcd_barrier(const XcdBarrier& b, int wave0) {
;     ...
;             else XB_SPIN(xb_ld(&bar[XB_TOPGEN]) == tg, bar);
;             __builtin_amdgcn_fence(__ATOMIC_ACQUIRE, "agent");
;             xb_add(&bar[XB_XGEN(b.x)], 1u);
;             asm volatile("s_waitcnt vmcnt(0)" ::: "memory");
.LBB0_147:
	s_or_b64 exec, exec, s[6:7]
	v_mov_b32_e32 v0, 0x2000
	v_mov_b32_e32 v1, 1
	s_waitcnt vmcnt(0)
	global_atomic_add v0, v1, s[4:5] offset:1024
	buffer_inv sc1
	s_waitcnt vmcnt(0)

; __device__ __forceinline__ unsigned xb_ld(unsigned* p)              { return __hip_atomic_load(p, __ATOMIC_RELAXED, __HIP_MEMORY_SCOPE_AGENT); }
; __device__ __forceinline__ unsigned xb_add(unsigned* p, unsigned v) { return __hip_atomic_fetch_add(p, v, __ATOMIC_RELAXED, __HIP_MEMORY_SCOPE_AGENT); }
; #define XB_SPIN(cond, bar) do { unsigned _sp = 0; while (cond) { __builtin_amdgcn_s_sleep(1); \
;     if ((++_sp & 255u) == 0u) { if (xb_ld(&(bar)[XB_TMO])) break; if (_sp > XB_SPIN_CAP) { atomicAdd(&(bar)[XB_TMO], 1u); break; } } } } while (0)
; __device__ __forceinline__ void xcd_barrier(const XcdBarrier& b, int wave0) {
;     ...
;             else XB_SPIN(xb_ld(&bar[XB_TOPGEN]) == tg, bar);
;             __builtin_amdgcn_fence(__ATOMIC_ACQUIRE, "agent");
;             xb_add(&bar[XB_XGEN(b.x)], 1u);
;             asm volatile("s_waitcnt vmcnt(0)" ::: "memory");
.LBB0_229:
	s_or_b64 exec, exec, s[6:7]
	v_mov_b32_e32 v0, 1
	v_mov_b32_e32 v1, 0x2000
	s_waitcnt vmcnt(0)
	global_atomic_add v1, v0, s[4:5] offset:1024
	buffer_inv sc1
	s_waitcnt vmcnt(0)

; __device__ __forceinline__ unsigned xb_ld(unsigned* p)              { return __hip_atomic_load(p, __ATOMIC_RELAXED, __HIP_MEMORY_SCOPE_AGENT); }
; __device__ __forceinline__ unsigned xb_add(unsigned* p, unsigned v) { return __hip_atomic_fetch_add(p, v, __ATOMIC_RELAXED, __HIP_MEMORY_SCOPE_AGENT); }
; #define XB_SPIN(cond, bar) do { unsigned _sp = 0; while (cond) { __builtin_amdgcn_s_sleep(1); \
;     if ((++_sp & 255u) == 0u) { if (xb_ld(&(bar)[XB_TMO])) break; if (_sp > XB_SPIN_CAP) { atomicAdd(&(bar)[XB_TMO], 1u); break; } } } } while (0)
; __device__ __forceinline__ void xcd_barrier(const XcdBarrier& b, int wave0) {
;     ...
;             else XB_SPIN(xb_ld(&bar[XB_TOPGEN]) == tg, bar);
;             __builtin_amdgcn_fence(__ATOMIC_ACQUIRE, "agent");
;             xb_add(&bar[XB_XGEN(b.x)], 1u);
;             asm volatile("s_waitcnt vmcnt(0)" ::: "memory");
.LBB0_386:
	s_or_b64 exec, exec, s[8:9]
	v_mov_b32_e32 v0, 1
	v_mov_b32_e32 v1, 0x2000
	s_waitcnt vmcnt(0)
	global_atomic_add v1, v0, s[6:7] offset:1024
	buffer_inv sc1
	s_waitcnt vmcnt(0)
